# sample attention: static XCD-aware item assignment (each XCD handles one (batch,head) so K/V stay L2-resident) replacing the atomic work queue
# speedup vs baseline: 1.1241x; 1.0102x over previous
.LBB0_229:
	v_readlane_b32 s4, v254, 63
	v_readlane_b32 s5, v255, 0
	s_and_b64 vcc, exec, s[4:5]
	s_cbranch_vccz .LBB0_235
	s_barrier
	s_mov_b64 s[4:5], exec
	v_readlane_b32 s20, v252, 26
	v_readlane_b32 s21, v252, 27
	s_and_b64 s[20:21], s[4:5], s[20:21]
	s_mov_b64 exec, s[20:21]
	s_cbranch_execz .LBB0_234
	s_mov_b64 s[24:25], exec
	v_mbcnt_lo_u32_b32 v0, s24, 0
	v_mbcnt_hi_u32_b32 v0, s25, v0
	v_cmp_eq_u32_e32 vcc, 0, v0
	s_and_saveexec_b64 s[20:21], vcc
	s_cbranch_execz .LBB0_233
	s_waitcnt lgkmcnt(0)
	ds_read_b32 v2, v196 offset:4
	v_readlane_b32 s99, v255, 12
	s_waitcnt lgkmcnt(0)
	v_readfirstlane_b32 s24, v2
	s_nop 3
	s_and_b32 s25, s99, 7
	s_lshl_b32 s25, s25, 6
	s_lshr_b32 s26, s99, 3
	s_or_b32 s25, s25, s26
	s_add_i32 s25, s25, 0x100
	s_cmpk_lt_u32 s99, 0x100
	s_cselect_b32 s26, 0, 1
	s_add_i32 s26, s26, s24
	s_add_i32 s24, s24, 1
	s_cmp_eq_u32 s26, 1
	s_cselect_b32 s98, s25, 0x300
	s_cmp_eq_u32 s26, 0
	s_cselect_b32 s98, s99, s98
	s_cmp_gt_u32 s26, 1
	s_cselect_b32 s24, 0, s24
	v_mov_b32_e32 v2, s24
	ds_write_b32 v196, v2 offset:4
	v_mov_b32_e32 v2, s98
